# softmax-shift maxima (max|qg|, max|kg|) computed once per wave in P0 from two per-lane loads and a DPP wave reduction, kept in two SGPRs; P3's preamble after grid barrier 3 (32 uniform loads + max cha
# speedup vs baseline: 1.0060x; 1.0060x over previous
; #define LAS __attribute__((address_space(3)))
; __device__ __forceinline__ void phase0(const Params& p, LAS unsigned char* lds, int tid, int lane, int wave) {
;     float* mod = (float*)(p.ws + WS_MOD);
;     const int ngemv = gridDim.x > 192 ? 192 : gridDim.x;
;     if (blockIdx.x < ngemv) {
;         LAS float* vecs = (LAS float*)lds; LAS float* red = (LAS float*)(lds + 32768);
;         f32x4 wv[16]; gemv_load(p.w_ada, NMOD, 32 * blockIdx.x, wv, tid);
;         for (int i = tid; i < 8192; i += 512) { const float v = p.c[i]; vecs[i] = v / (1.f + __expf(-v)); }
;         __syncthreads();
;         for (int it = blockIdx.x; it < 192; it += ngemv) { if (it != (int)blockIdx.x) gemv_load(p.w_ada, NMOD, 32 * it, wv, tid); gemv_item(wv, NMOD, 32 * it, p.b_ada, vecs, red, mod, tid); }
;     } else {
;         transposes(p, lds, 0, NIT_IN, (blockIdx.x - 192) * 8 + wave, (gridDim.x - 192) * 8, lane, wave);
; __device__ __forceinline__ void phase3(const Params& p, LAS unsigned char* lds, int tid, int lane, int wave) {
;     ...
;     for (int i = 0; i < 64; ++i) { mq = fmaxf(mq, fabsf(p.qg[i])); mk = fmaxf(mk, fabsf(p.kg[i])); }
.LBB0_6:
	s_or_b64 exec, exec, s[6:7]
	s_load_dwordx2 s[4:5], s[96:97], 0
	s_load_dwordx2 s[6:7], s[96:97], 8
	s_load_dwordx2 s[14:15], s[96:97], 16
	s_load_dwordx2 s[12:13], s[96:97], 24
	s_load_dwordx2 s[8:9], s[96:97], 32
	s_load_dwordx2 s[18:19], s[96:97], 40
	s_load_dwordx2 s[10:11], s[96:97], 48
	s_load_dwordx2 s[20:21], s[96:97], 56
	s_load_dwordx2 s[22:23], s[96:97], 64
	s_load_dwordx2 s[28:29], s[96:97], 72
	s_load_dwordx2 s[30:31], s[96:97], 80
	s_load_dwordx2 s[34:35], s[96:97], 88
	s_load_dwordx2 s[36:37], s[96:97], 96
	s_load_dwordx2 s[38:39], s[96:97], 104
	s_load_dwordx2 s[40:41], s[96:97], 112
	s_load_dwordx2 s[42:43], s[96:97], 120
	s_load_dwordx2 s[16:17], s[96:97], 128
	s_waitcnt lgkmcnt(0)
	v_and_b32_e32 v200, 63, v208
	v_lshlrev_b32_e32 v200, 2, v200
	global_load_dword v201, v200, s[20:21]
	global_load_dword v202, v200, s[22:23]
	s_lshr_b32 s58, s3, 6
	s_min_u32 s4, s26, 0xc0
	v_and_b32_e32 v154, 63, v208
	s_cmp_ge_u32 s2, s4
	s_mov_b64 s[8:9], -1
	s_cbranch_scc0 .LBB0_19
	s_lshl_b32 s0, s2, 3
	s_add_i32 s0, s0, s58
	s_add_i32 s5, s0, 0xfffffa00
	s_cmpk_gt_i32 s5, 0x5ff
	s_cbranch_scc1 .LBB0_18
	s_lshl_b32 s22, s26, 3
	s_mul_i32 s0, s58, 0x2200
	v_lshlrev_b32_e32 v3, 3, v208
	s_addk_i32 s22, 0xfa00
	s_add_i32 s0, s0, 0
	v_lshrrev_b32_e32 v2, 3, v154
	v_and_b32_e32 v3, 56, v3
	v_lshrrev_b32_e32 v4, 5, v154
	v_and_b32_e32 v0, 31, v208
	v_mul_u32_u24_e32 v3, 0x84, v3
	v_lshlrev_b32_e32 v5, 2, v2
	s_add_u32 s8, s16, 0x600000
	v_lshl_add_u32 v7, v0, 2, s0
	v_mul_u32_u24_e32 v8, 0x84, v4
	v_add3_u32 v5, s0, v3, v5
	s_addc_u32 s0, s17, 0
	v_lshlrev_b32_e32 v2, 11, v2
	v_and_b32_e32 v3, 7, v208
	s_and_b32 s9, s0, 0xffff
	v_lshl_or_b32 v2, s5, 16, v2
	v_lshlrev_b32_e32 v3, 4, v3
	s_mov_b32 s0, 0xc000
	v_add_u32_e32 v7, v7, v8
	v_mov_b32_e32 v1, 0
	s_mov_b32 s11, 0x20000
	s_brev_b32 s10, -2
	v_or3_b32 v6, v2, v3, s0
	s_lshl_b32 s23, s22, 16
	s_lshl_b32 s28, s5, 5
	s_lshl_b32 s29, s22, 5
	s_movk_i32 s30, 0x608
	s_movk_i32 s31, 0x3020
	v_mov_b64_e32 v[2:3], s[18:19]
	v_lshlrev_b32_e32 v0, 2, v0
	v_add_u32_e32 v8, 0x400, v7
	v_add_u32_e32 v9, 0x800, v7
	v_add_u32_e32 v10, 0xc00, v7
	v_add_u32_e32 v11, 0x1000, v7
	v_add_u32_e32 v12, 0x1400, v7
	v_add_u32_e32 v13, 0x1800, v7
	v_add_u32_e32 v14, 0x1c00, v7
	s_cmpk_lg_i32 s26, 0x100
	s_cbranch_scc1 .LBB0_10
	v_readfirstlane_b32 s38, v2
	v_readfirstlane_b32 s39, v3
	v_mul_u32_u24_e32 v15, 0x3020, v4
	v_add_u32_e32 v15, v15, v0
	s_add_i32 s40, s5, 0
	s_lshl_b32 s41, s40, 5
	s_mul_hi_i32 s42, s40, 0x2aaaaaab
	s_lshr_b32 s43, s42, 31
	s_ashr_i32 s50, s42, 4
	s_add_i32 s50, s50, s43
	s_mul_i32 s42, s50, 0xffffffa0
	s_mul_i32 s43, s50, 0xfffff400
	s_add_i32 s42, s40, s42
	s_add_i32 s44, s41, s43
	s_ashr_i32 s45, s42, 3
	s_and_b32 s46, s44, 0x60
	s_cmp_gt_i32 s45, 5
	s_cbranch_scc0 .Lp0h_low0
	s_and_b32 s47, s44, 0xe0
	s_cmp_gt_u32 s45, 9
	s_cbranch_scc0 .Lp0h_mid0
	s_and_b32 s48, s44, 0xffffff00
	s_or_b32 s48, s48, s47
	s_add_i32 s53, s48, 0xfffffe08
	s_branch .Lp0h_done0

; __device__ __forceinline__ void phase3(const Params& p, LAS unsigned char* lds, int tid, int lane, int wave) {
;     ...
;     for (int i = 0; i < 64; ++i) { mq = fmaxf(mq, fabsf(p.qg[i])); mk = fmaxf(mk, fabsf(p.kg[i])); }
;     const float mshift = 8.f * LOG2E * 1.03f * mq * mk;
.LBB0_32:
	s_waitcnt vmcnt(0)
	v_and_b32_e32 v201, 0x7fffffff, v201
	v_and_b32_e32 v202, 0x7fffffff, v202
	s_nop 1
	v_max_f32_dpp v201, v201, v201 quad_perm:[1,0,3,2] row_mask:0xf bank_mask:0xf bound_ctrl:1
	v_max_f32_dpp v202, v202, v202 quad_perm:[1,0,3,2] row_mask:0xf bank_mask:0xf bound_ctrl:1
	s_nop 1
	v_max_f32_dpp v201, v201, v201 quad_perm:[2,3,0,1] row_mask:0xf bank_mask:0xf bound_ctrl:1
	v_max_f32_dpp v202, v202, v202 quad_perm:[2,3,0,1] row_mask:0xf bank_mask:0xf bound_ctrl:1
	s_nop 1
	v_max_f32_dpp v201, v201, v201 row_ror:4 row_mask:0xf bank_mask:0xf bound_ctrl:1
	v_max_f32_dpp v202, v202, v202 row_ror:4 row_mask:0xf bank_mask:0xf bound_ctrl:1
	s_nop 1
	v_max_f32_dpp v201, v201, v201 row_ror:8 row_mask:0xf bank_mask:0xf bound_ctrl:1
	v_max_f32_dpp v202, v202, v202 row_ror:8 row_mask:0xf bank_mask:0xf bound_ctrl:1
	s_nop 1
	v_readlane_b32 s20, v201, 0
	v_readlane_b32 s21, v201, 16
	v_readlane_b32 s22, v201, 32
	v_readlane_b32 s23, v201, 48
	v_mov_b32_e32 v203, s20
	v_max_f32_e32 v203, s21, v203
	v_max_f32_e32 v203, s22, v203
	v_max_f32_e32 v203, s23, v203
	s_nop 0
	v_readfirstlane_b32 s98, v203
	v_readlane_b32 s20, v202, 0
	v_readlane_b32 s21, v202, 16
	v_readlane_b32 s22, v202, 32
	v_readlane_b32 s23, v202, 48
	v_mov_b32_e32 v203, s20
	v_max_f32_e32 v203, s21, v203
	v_max_f32_e32 v203, s22, v203
	v_max_f32_e32 v203, s23, v203
	s_nop 0
	v_readfirstlane_b32 s99, v203
	v_readlane_b32 s0, v255, 3
	v_readlane_b32 s1, v255, 4
	s_barrier
	v_readfirstlane_b32 s4, v208
	s_cmp_lg_u32 s4, 64
	s_cbranch_scc1 .Lgb1_noinv
	buffer_inv sc1
	s_waitcnt vmcnt(0)

; __device__ __forceinline__ void phase3(const Params& p, LAS unsigned char* lds, int tid, int lane, int wave) {
;     float mq = 0.f, mk = 0.f;
;     for (int i = 0; i < 64; ++i) { mq = fmaxf(mq, fabsf(p.qg[i])); mk = fmaxf(mk, fabsf(p.kg[i])); }
;     const float mshift = 8.f * LOG2E * 1.03f * mq * mk;
;     const int G = gridDim.x, bx = blockIdx.x; const int vcu = (G % 8 == 0) ? (bx % 8) * (G / 8) + bx / 8 : bx;
.LBB0_346:
	v_mov_b32_e32 v1, s98
	v_mov_b32_e32 v0, s99
	s_movk_i32 s16, 0x100
	s_and_b32 s0, s26, 7
	s_cmp_eq_u32 s0, 0
	s_mov_b32 s3, s2
	s_cbranch_scc1 .LBB0_349
	s_cmpk_gt_i32 s3, 0xff
	s_cbranch_scc0 .LBB0_350
	s_branch .LBB0_382

; __global__ void __launch_bounds__(512, 2) hymba_mega(Params p_arg) {
	.amdhsa_kernel _Z10hymba_mega6Params
		.amdhsa_group_segment_fixed_size 0
		.amdhsa_private_segment_fixed_size 0
		.amdhsa_kernarg_size 392
		.amdhsa_user_sgpr_count 2
		.amdhsa_user_sgpr_dispatch_ptr 0
		.amdhsa_user_sgpr_queue_ptr 0
		.amdhsa_user_sgpr_kernarg_segment_ptr 1
		.amdhsa_user_sgpr_dispatch_id 0
		.amdhsa_user_sgpr_kernarg_preload_length 0
		.amdhsa_user_sgpr_kernarg_preload_offset 0
		.amdhsa_user_sgpr_private_segment_size 0
		.amdhsa_uses_dynamic_stack 0
		.amdhsa_enable_private_segment 0
		.amdhsa_system_sgpr_workgroup_id_x 1
		.amdhsa_system_sgpr_workgroup_id_y 0
		.amdhsa_system_sgpr_workgroup_id_z 0
		.amdhsa_system_sgpr_workgroup_info 0
		.amdhsa_system_vgpr_workitem_id 2
		.amdhsa_next_free_vgpr 256
		.amdhsa_next_free_sgpr 100
		.amdhsa_accum_offset 256
		.amdhsa_reserve_vcc 1
		.amdhsa_float_round_mode_32 0
		.amdhsa_float_round_mode_16_64 0
		.amdhsa_float_denorm_mode_32 3
		.amdhsa_float_denorm_mode_16_64 3
		.amdhsa_dx10_clamp 1
		.amdhsa_ieee_mode 1
		.amdhsa_fp16_overflow 0
		.amdhsa_tg_split 0
		.amdhsa_exception_fp_ieee_invalid_op 0
		.amdhsa_exception_fp_denorm_src 0
		.amdhsa_exception_fp_ieee_div_zero 0
		.amdhsa_exception_fp_ieee_overflow 0
		.amdhsa_exception_fp_ieee_underflow 0
		.amdhsa_exception_fp_ieee_inexact 0
		.amdhsa_exception_int_div_zero 0
	.end_amdhsa_kernel

; __global__ void __launch_bounds__(512, 2) hymba_mega(Params p_arg) {
amdhsa.kernels:
  - .agpr_count:     0
    .args:
      - .offset:         0
        .size:           136
        .value_kind:     by_value
      - .offset:         136
        .size:           4
        .value_kind:     hidden_block_count_x
      - .offset:         140
        .size:           4
        .value_kind:     hidden_block_count_y
      - .offset:         144
        .size:           4
        .value_kind:     hidden_block_count_z
      - .offset:         148
        .size:           2
        .value_kind:     hidden_group_size_x
      - .offset:         150
        .size:           2
        .value_kind:     hidden_group_size_y
      - .offset:         152
        .size:           2
        .value_kind:     hidden_group_size_z
      - .offset:         154
        .size:           2
        .value_kind:     hidden_remainder_x
      - .offset:         156
        .size:           2
        .value_kind:     hidden_remainder_y
      - .offset:         158
        .size:           2
        .value_kind:     hidden_remainder_z
      - .offset:         176
        .size:           8
        .value_kind:     hidden_global_offset_x
      - .offset:         184
        .size:           8
        .value_kind:     hidden_global_offset_y
      - .offset:         192
        .size:           8
        .value_kind:     hidden_global_offset_z
      - .offset:         200
        .size:           2
        .value_kind:     hidden_grid_dims
      - .offset:         224
        .size:           8
        .value_kind:     hidden_multigrid_sync_arg
      - .offset:         256
        .size:           4
        .value_kind:     hidden_dynamic_lds_size
    .group_segment_fixed_size: 0
    .kernarg_segment_align: 8
    .kernarg_segment_size: 392
    .language:       OpenCL C
    .language_version:
      - 2
      - 0
    .max_flat_workgroup_size: 512
    .name:           _Z10hymba_mega6Params
    .private_segment_fixed_size: 0
    .sgpr_count:     106
    .sgpr_spill_count: 13
    .symbol:         _Z10hymba_mega6Params.kd
    .uniform_work_group_size: 1
    .uses_dynamic_stack: false
    .vgpr_count:     256
    .vgpr_spill_count: 0
    .wavefront_size: 64
